# EpiSwiglu epilogue hand-written: batched silu stages, folded scales, rstd reads hoisted
# speedup vs baseline: 1.0269x; 1.0054x over previous
.LBB0_1955:
	s_mov_b32 s98, 0
	s_cmp_eq_u32 s22, s39
	s_cbranch_scc1 .Lswi_fast
	s_movk_i32 s98, 0x400
	s_cmp_eq_u32 s22, s38
	s_cbranch_scc1 .Lswi_fast
	s_movk_i32 s98, 0x800
	s_cmp_eq_u32 s22, s37
	s_cbranch_scc1 .Lswi_fast
	s_movk_i32 s98, 0xc00
	s_cmp_eq_u32 s22, s36
	s_cbranch_scc0 .Lswi_slow
.Lswi_fast:
	v_add_u32_e32 v140, s98, v147
	ds_read_b32 v150, v140
	ds_read_b32 v151, v140 offset:64
	ds_read_b32 v152, v140 offset:128
	ds_read_b32 v153, v140 offset:192
	ds_read_b32 v154, v140 offset:512
	ds_read_b32 v155, v140 offset:576
	ds_read_b32 v156, v140 offset:640
	ds_read_b32 v157, v140 offset:704
	v_lshl_add_u32 v141, s22, 8, v145
	v_mul_u32_u24_e32 v141, s77, v141
	v_lshl_or_b32 v142, s4, 7, v148
	v_lshl_add_u32 v141, v142, 1, v141
	s_waitcnt lgkmcnt(7)
	v_mul_f32_e32 v158, 0xbfb8aa3b, v150
	v_mul_f32_e32 v159, v150, v150
	v_mul_f32_e32 v160, v158, v126
	v_mul_f32_e32 v161, v158, v127
	v_mul_f32_e32 v162, v158, v128
	v_mul_f32_e32 v163, v158, v129
	v_mul_f32_e32 v164, v158, v118
	v_mul_f32_e32 v165, v158, v119
	v_mul_f32_e32 v166, v158, v120
	v_mul_f32_e32 v167, v158, v121
	v_exp_f32_e32 v160, v160
	v_exp_f32_e32 v161, v161
	v_exp_f32_e32 v162, v162
	v_exp_f32_e32 v163, v163
	v_exp_f32_e32 v164, v164
	v_exp_f32_e32 v165, v165
	v_exp_f32_e32 v166, v166
	v_exp_f32_e32 v167, v167
	v_add_f32_e32 v160, 1.0, v160
	v_add_f32_e32 v161, 1.0, v161
	v_add_f32_e32 v162, 1.0, v162
	v_add_f32_e32 v163, 1.0, v163
	v_add_f32_e32 v164, 1.0, v164
	v_add_f32_e32 v165, 1.0, v165
	v_add_f32_e32 v166, 1.0, v166
	v_add_f32_e32 v167, 1.0, v167
	v_rcp_f32_e32 v160, v160
	v_rcp_f32_e32 v161, v161
	v_rcp_f32_e32 v162, v162
	v_rcp_f32_e32 v163, v163
	v_rcp_f32_e32 v164, v164
	v_rcp_f32_e32 v165, v165
	v_rcp_f32_e32 v166, v166
	v_rcp_f32_e32 v167, v167
	v_mul_f32_e32 v126, v126, v122
	v_mul_f32_e32 v127, v127, v123
	v_mul_f32_e32 v128, v128, v124
	v_mul_f32_e32 v129, v129, v125
	v_mul_f32_e32 v118, v118, v114
	v_mul_f32_e32 v119, v119, v115
	v_mul_f32_e32 v120, v120, v116
	v_mul_f32_e32 v121, v121, v117
	v_mul_f32_e32 v160, v159, v160
	v_mul_f32_e32 v161, v159, v161
	v_mul_f32_e32 v162, v159, v162
	v_mul_f32_e32 v163, v159, v163
	v_mul_f32_e32 v164, v159, v164
	v_mul_f32_e32 v165, v159, v165
	v_mul_f32_e32 v166, v159, v166
	v_mul_f32_e32 v167, v159, v167
	v_mul_f32_e32 v126, v126, v160
	v_mul_f32_e32 v127, v127, v161
	v_mul_f32_e32 v128, v128, v162
	v_mul_f32_e32 v129, v129, v163
	v_mul_f32_e32 v118, v118, v164
	v_mul_f32_e32 v119, v119, v165
	v_mul_f32_e32 v120, v120, v166
	v_mul_f32_e32 v121, v121, v167
	v_cvt_pk_bf16_f32 v160, v126, v127
	v_cvt_pk_bf16_f32 v161, v128, v129
	v_cvt_pk_bf16_f32 v162, v118, v119
	v_cvt_pk_bf16_f32 v163, v120, v121
	global_store_dwordx4 v141, v[160:163], s[10:11]
	s_waitcnt lgkmcnt(6)
	v_mul_f32_e32 v158, 0xbfb8aa3b, v151
	v_mul_f32_e32 v159, v151, v151
	v_mul_f32_e32 v168, v158, v108
	v_mul_f32_e32 v169, v158, v109
	v_mul_f32_e32 v170, v158, v110
	v_mul_f32_e32 v171, v158, v111
	v_mul_f32_e32 v172, v158, v100
	v_mul_f32_e32 v173, v158, v101
	v_mul_f32_e32 v174, v158, v102
	v_mul_f32_e32 v175, v158, v103
	v_exp_f32_e32 v168, v168
	v_exp_f32_e32 v169, v169
	v_exp_f32_e32 v170, v170
	v_exp_f32_e32 v171, v171
	v_exp_f32_e32 v172, v172
	v_exp_f32_e32 v173, v173
	v_exp_f32_e32 v174, v174
	v_exp_f32_e32 v175, v175
	v_add_f32_e32 v168, 1.0, v168
	v_add_f32_e32 v169, 1.0, v169
	v_add_f32_e32 v170, 1.0, v170
	v_add_f32_e32 v171, 1.0, v171
	v_add_f32_e32 v172, 1.0, v172
	v_add_f32_e32 v173, 1.0, v173
	v_add_f32_e32 v174, 1.0, v174
	v_add_f32_e32 v175, 1.0, v175
	v_rcp_f32_e32 v168, v168
	v_rcp_f32_e32 v169, v169
	v_rcp_f32_e32 v170, v170
	v_rcp_f32_e32 v171, v171
	v_rcp_f32_e32 v172, v172
	v_rcp_f32_e32 v173, v173
	v_rcp_f32_e32 v174, v174
	v_rcp_f32_e32 v175, v175
	v_mul_f32_e32 v108, v108, v104
	v_mul_f32_e32 v109, v109, v105
	v_mul_f32_e32 v110, v110, v106
	v_mul_f32_e32 v111, v111, v107
	v_mul_f32_e32 v100, v100, v96
	v_mul_f32_e32 v101, v101, v97
	v_mul_f32_e32 v102, v102, v98
	v_mul_f32_e32 v103, v103, v99
	v_mul_f32_e32 v168, v159, v168
	v_mul_f32_e32 v169, v159, v169
	v_mul_f32_e32 v170, v159, v170
	v_mul_f32_e32 v171, v159, v171
	v_mul_f32_e32 v172, v159, v172
	v_mul_f32_e32 v173, v159, v173
	v_mul_f32_e32 v174, v159, v174
	v_mul_f32_e32 v175, v159, v175
	v_mul_f32_e32 v108, v108, v168
	v_mul_f32_e32 v109, v109, v169
	v_mul_f32_e32 v110, v110, v170
	v_mul_f32_e32 v111, v111, v171
	v_mul_f32_e32 v100, v100, v172
	v_mul_f32_e32 v101, v101, v173
	v_mul_f32_e32 v102, v102, v174
	v_mul_f32_e32 v103, v103, v175
	v_cvt_pk_bf16_f32 v168, v108, v109
	v_cvt_pk_bf16_f32 v169, v110, v111
	v_cvt_pk_bf16_f32 v170, v100, v101
	v_cvt_pk_bf16_f32 v171, v102, v103
	v_add_u32_e32 v143, 0x16000, v141
	global_store_dwordx4 v143, v[168:171], s[10:11]
	s_waitcnt lgkmcnt(5)
	v_mul_f32_e32 v158, 0xbfb8aa3b, v152
	v_mul_f32_e32 v159, v152, v152
	v_mul_f32_e32 v160, v158, v92
	v_mul_f32_e32 v161, v158, v93
	v_mul_f32_e32 v162, v158, v94
	v_mul_f32_e32 v163, v158, v95
	v_mul_f32_e32 v164, v158, v84
	v_mul_f32_e32 v165, v158, v85
	v_mul_f32_e32 v166, v158, v86
	v_mul_f32_e32 v167, v158, v87
	v_exp_f32_e32 v160, v160
	v_exp_f32_e32 v161, v161
	v_exp_f32_e32 v162, v162
	v_exp_f32_e32 v163, v163
	v_exp_f32_e32 v164, v164
	v_exp_f32_e32 v165, v165
	v_exp_f32_e32 v166, v166
	v_exp_f32_e32 v167, v167
	v_add_f32_e32 v160, 1.0, v160
	v_add_f32_e32 v161, 1.0, v161
	v_add_f32_e32 v162, 1.0, v162
	v_add_f32_e32 v163, 1.0, v163
	v_add_f32_e32 v164, 1.0, v164
	v_add_f32_e32 v165, 1.0, v165
	v_add_f32_e32 v166, 1.0, v166
	v_add_f32_e32 v167, 1.0, v167
	v_rcp_f32_e32 v160, v160
	v_rcp_f32_e32 v161, v161
	v_rcp_f32_e32 v162, v162
	v_rcp_f32_e32 v163, v163
	v_rcp_f32_e32 v164, v164
	v_rcp_f32_e32 v165, v165
	v_rcp_f32_e32 v166, v166
	v_rcp_f32_e32 v167, v167
	v_mul_f32_e32 v92, v92, v88
	v_mul_f32_e32 v93, v93, v89
	v_mul_f32_e32 v94, v94, v90
	v_mul_f32_e32 v95, v95, v91
	v_mul_f32_e32 v84, v84, v80
	v_mul_f32_e32 v85, v85, v81
	v_mul_f32_e32 v86, v86, v82
	v_mul_f32_e32 v87, v87, v83
	v_mul_f32_e32 v160, v159, v160
	v_mul_f32_e32 v161, v159, v161
	v_mul_f32_e32 v162, v159, v162
	v_mul_f32_e32 v163, v159, v163
	v_mul_f32_e32 v164, v159, v164
	v_mul_f32_e32 v165, v159, v165
	v_mul_f32_e32 v166, v159, v166
	v_mul_f32_e32 v167, v159, v167
	v_mul_f32_e32 v92, v92, v160
	v_mul_f32_e32 v93, v93, v161
	v_mul_f32_e32 v94, v94, v162
	v_mul_f32_e32 v95, v95, v163
	v_mul_f32_e32 v84, v84, v164
	v_mul_f32_e32 v85, v85, v165
	v_mul_f32_e32 v86, v86, v166
	v_mul_f32_e32 v87, v87, v167
	v_cvt_pk_bf16_f32 v160, v92, v93
	v_cvt_pk_bf16_f32 v161, v94, v95
	v_cvt_pk_bf16_f32 v162, v84, v85
	v_cvt_pk_bf16_f32 v163, v86, v87
	v_add_u32_e32 v144, 0x2c000, v141
	global_store_dwordx4 v144, v[160:163], s[10:11]
	s_waitcnt lgkmcnt(4)
	v_mul_f32_e32 v158, 0xbfb8aa3b, v153
	v_mul_f32_e32 v159, v153, v153
	v_mul_f32_e32 v168, v158, v76
	v_mul_f32_e32 v169, v158, v77
	v_mul_f32_e32 v170, v158, v78
	v_mul_f32_e32 v171, v158, v79
	v_mul_f32_e32 v172, v158, v68
	v_mul_f32_e32 v173, v158, v69
	v_mul_f32_e32 v174, v158, v70
	v_mul_f32_e32 v175, v158, v71
	v_exp_f32_e32 v168, v168
	v_exp_f32_e32 v169, v169
	v_exp_f32_e32 v170, v170
	v_exp_f32_e32 v171, v171
	v_exp_f32_e32 v172, v172
	v_exp_f32_e32 v173, v173
	v_exp_f32_e32 v174, v174
	v_exp_f32_e32 v175, v175
	v_add_f32_e32 v168, 1.0, v168
	v_add_f32_e32 v169, 1.0, v169
	v_add_f32_e32 v170, 1.0, v170
	v_add_f32_e32 v171, 1.0, v171
	v_add_f32_e32 v172, 1.0, v172
	v_add_f32_e32 v173, 1.0, v173
	v_add_f32_e32 v174, 1.0, v174
	v_add_f32_e32 v175, 1.0, v175
	v_rcp_f32_e32 v168, v168
	v_rcp_f32_e32 v169, v169
	v_rcp_f32_e32 v170, v170
	v_rcp_f32_e32 v171, v171
	v_rcp_f32_e32 v172, v172
	v_rcp_f32_e32 v173, v173
	v_rcp_f32_e32 v174, v174
	v_rcp_f32_e32 v175, v175
	v_mul_f32_e32 v76, v76, v72
	v_mul_f32_e32 v77, v77, v73
	v_mul_f32_e32 v78, v78, v74
	v_mul_f32_e32 v79, v79, v75
	v_mul_f32_e32 v68, v68, v64
	v_mul_f32_e32 v69, v69, v65
	v_mul_f32_e32 v70, v70, v66
	v_mul_f32_e32 v71, v71, v67
	v_mul_f32_e32 v168, v159, v168
	v_mul_f32_e32 v169, v159, v169
	v_mul_f32_e32 v170, v159, v170
	v_mul_f32_e32 v171, v159, v171
	v_mul_f32_e32 v172, v159, v172
	v_mul_f32_e32 v173, v159, v173
	v_mul_f32_e32 v174, v159, v174
	v_mul_f32_e32 v175, v159, v175
	v_mul_f32_e32 v76, v76, v168
	v_mul_f32_e32 v77, v77, v169
	v_mul_f32_e32 v78, v78, v170
	v_mul_f32_e32 v79, v79, v171
	v_mul_f32_e32 v68, v68, v172
	v_mul_f32_e32 v69, v69, v173
	v_mul_f32_e32 v70, v70, v174
	v_mul_f32_e32 v71, v71, v175
	v_cvt_pk_bf16_f32 v168, v76, v77
	v_cvt_pk_bf16_f32 v169, v78, v79
	v_cvt_pk_bf16_f32 v170, v68, v69
	v_cvt_pk_bf16_f32 v171, v70, v71
	v_add_u32_e32 v143, 0x42000, v141
	global_store_dwordx4 v143, v[168:171], s[10:11]
	s_waitcnt lgkmcnt(3)
	v_mul_f32_e32 v158, 0xbfb8aa3b, v154
	v_mul_f32_e32 v159, v154, v154
	v_mul_f32_e32 v160, v158, v60
	v_mul_f32_e32 v161, v158, v61
	v_mul_f32_e32 v162, v158, v62
	v_mul_f32_e32 v163, v158, v63
	v_mul_f32_e32 v164, v158, v52
	v_mul_f32_e32 v165, v158, v53
	v_mul_f32_e32 v166, v158, v54
	v_mul_f32_e32 v167, v158, v55
	v_exp_f32_e32 v160, v160
	v_exp_f32_e32 v161, v161
	v_exp_f32_e32 v162, v162
	v_exp_f32_e32 v163, v163
	v_exp_f32_e32 v164, v164
	v_exp_f32_e32 v165, v165
	v_exp_f32_e32 v166, v166
	v_exp_f32_e32 v167, v167
	v_add_f32_e32 v160, 1.0, v160
	v_add_f32_e32 v161, 1.0, v161
	v_add_f32_e32 v162, 1.0, v162
	v_add_f32_e32 v163, 1.0, v163
	v_add_f32_e32 v164, 1.0, v164
	v_add_f32_e32 v165, 1.0, v165
	v_add_f32_e32 v166, 1.0, v166
	v_add_f32_e32 v167, 1.0, v167
	v_rcp_f32_e32 v160, v160
	v_rcp_f32_e32 v161, v161
	v_rcp_f32_e32 v162, v162
	v_rcp_f32_e32 v163, v163
	v_rcp_f32_e32 v164, v164
	v_rcp_f32_e32 v165, v165
	v_rcp_f32_e32 v166, v166
	v_rcp_f32_e32 v167, v167
	v_mul_f32_e32 v60, v60, v56
	v_mul_f32_e32 v61, v61, v57
	v_mul_f32_e32 v62, v62, v58
	v_mul_f32_e32 v63, v63, v59
	v_mul_f32_e32 v52, v52, v48
	v_mul_f32_e32 v53, v53, v49
	v_mul_f32_e32 v54, v54, v50
	v_mul_f32_e32 v55, v55, v51
	v_mul_f32_e32 v160, v159, v160
	v_mul_f32_e32 v161, v159, v161
	v_mul_f32_e32 v162, v159, v162
	v_mul_f32_e32 v163, v159, v163
	v_mul_f32_e32 v164, v159, v164
	v_mul_f32_e32 v165, v159, v165
	v_mul_f32_e32 v166, v159, v166
	v_mul_f32_e32 v167, v159, v167
	v_mul_f32_e32 v60, v60, v160
	v_mul_f32_e32 v61, v61, v161
	v_mul_f32_e32 v62, v62, v162
	v_mul_f32_e32 v63, v63, v163
	v_mul_f32_e32 v52, v52, v164
	v_mul_f32_e32 v53, v53, v165
	v_mul_f32_e32 v54, v54, v166
	v_mul_f32_e32 v55, v55, v167
	v_cvt_pk_bf16_f32 v160, v60, v61
	v_cvt_pk_bf16_f32 v161, v62, v63
	v_cvt_pk_bf16_f32 v162, v52, v53
	v_cvt_pk_bf16_f32 v163, v54, v55
	v_add_u32_e32 v144, 0xb0000, v141
	global_store_dwordx4 v144, v[160:163], s[10:11]
	s_waitcnt lgkmcnt(2)
	v_mul_f32_e32 v158, 0xbfb8aa3b, v155
	v_mul_f32_e32 v159, v155, v155
	v_mul_f32_e32 v168, v158, v44
	v_mul_f32_e32 v169, v158, v45
	v_mul_f32_e32 v170, v158, v46
	v_mul_f32_e32 v171, v158, v47
	v_mul_f32_e32 v172, v158, v36
	v_mul_f32_e32 v173, v158, v37
	v_mul_f32_e32 v174, v158, v38
	v_mul_f32_e32 v175, v158, v39
	v_exp_f32_e32 v168, v168
	v_exp_f32_e32 v169, v169
	v_exp_f32_e32 v170, v170
	v_exp_f32_e32 v171, v171
	v_exp_f32_e32 v172, v172
	v_exp_f32_e32 v173, v173
	v_exp_f32_e32 v174, v174
	v_exp_f32_e32 v175, v175
	v_add_f32_e32 v168, 1.0, v168
	v_add_f32_e32 v169, 1.0, v169
	v_add_f32_e32 v170, 1.0, v170
	v_add_f32_e32 v171, 1.0, v171
	v_add_f32_e32 v172, 1.0, v172
	v_add_f32_e32 v173, 1.0, v173
	v_add_f32_e32 v174, 1.0, v174
	v_add_f32_e32 v175, 1.0, v175
	v_rcp_f32_e32 v168, v168
	v_rcp_f32_e32 v169, v169
	v_rcp_f32_e32 v170, v170
	v_rcp_f32_e32 v171, v171
	v_rcp_f32_e32 v172, v172
	v_rcp_f32_e32 v173, v173
	v_rcp_f32_e32 v174, v174
	v_rcp_f32_e32 v175, v175
	v_mul_f32_e32 v44, v44, v40
	v_mul_f32_e32 v45, v45, v41
	v_mul_f32_e32 v46, v46, v42
	v_mul_f32_e32 v47, v47, v43
	v_mul_f32_e32 v36, v36, v32
	v_mul_f32_e32 v37, v37, v33
	v_mul_f32_e32 v38, v38, v34
	v_mul_f32_e32 v39, v39, v35
	v_mul_f32_e32 v168, v159, v168
	v_mul_f32_e32 v169, v159, v169
	v_mul_f32_e32 v170, v159, v170
	v_mul_f32_e32 v171, v159, v171
	v_mul_f32_e32 v172, v159, v172
	v_mul_f32_e32 v173, v159, v173
	v_mul_f32_e32 v174, v159, v174
	v_mul_f32_e32 v175, v159, v175
	v_mul_f32_e32 v44, v44, v168
	v_mul_f32_e32 v45, v45, v169
	v_mul_f32_e32 v46, v46, v170
	v_mul_f32_e32 v47, v47, v171
	v_mul_f32_e32 v36, v36, v172
	v_mul_f32_e32 v37, v37, v173
	v_mul_f32_e32 v38, v38, v174
	v_mul_f32_e32 v39, v39, v175
	v_cvt_pk_bf16_f32 v168, v44, v45
	v_cvt_pk_bf16_f32 v169, v46, v47
	v_cvt_pk_bf16_f32 v170, v36, v37
	v_cvt_pk_bf16_f32 v171, v38, v39
	v_add_u32_e32 v143, 0xc6000, v141
	global_store_dwordx4 v143, v[168:171], s[10:11]
	s_waitcnt lgkmcnt(1)
	v_mul_f32_e32 v158, 0xbfb8aa3b, v156
	v_mul_f32_e32 v159, v156, v156
	v_mul_f32_e32 v160, v158, v28
	v_mul_f32_e32 v161, v158, v29
	v_mul_f32_e32 v162, v158, v30
	v_mul_f32_e32 v163, v158, v31
	v_mul_f32_e32 v164, v158, v20
	v_mul_f32_e32 v165, v158, v21
	v_mul_f32_e32 v166, v158, v22
	v_mul_f32_e32 v167, v158, v23
	v_exp_f32_e32 v160, v160
	v_exp_f32_e32 v161, v161
	v_exp_f32_e32 v162, v162
	v_exp_f32_e32 v163, v163
	v_exp_f32_e32 v164, v164
	v_exp_f32_e32 v165, v165
	v_exp_f32_e32 v166, v166
	v_exp_f32_e32 v167, v167
	v_add_f32_e32 v160, 1.0, v160
	v_add_f32_e32 v161, 1.0, v161
	v_add_f32_e32 v162, 1.0, v162
	v_add_f32_e32 v163, 1.0, v163
	v_add_f32_e32 v164, 1.0, v164
	v_add_f32_e32 v165, 1.0, v165
	v_add_f32_e32 v166, 1.0, v166
	v_add_f32_e32 v167, 1.0, v167
	v_rcp_f32_e32 v160, v160
	v_rcp_f32_e32 v161, v161
	v_rcp_f32_e32 v162, v162
	v_rcp_f32_e32 v163, v163
	v_rcp_f32_e32 v164, v164
	v_rcp_f32_e32 v165, v165
	v_rcp_f32_e32 v166, v166
	v_rcp_f32_e32 v167, v167
	v_mul_f32_e32 v28, v28, v24
	v_mul_f32_e32 v29, v29, v25
	v_mul_f32_e32 v30, v30, v26
	v_mul_f32_e32 v31, v31, v27
	v_mul_f32_e32 v20, v20, v16
	v_mul_f32_e32 v21, v21, v17
	v_mul_f32_e32 v22, v22, v18
	v_mul_f32_e32 v23, v23, v19
	v_mul_f32_e32 v160, v159, v160
	v_mul_f32_e32 v161, v159, v161
	v_mul_f32_e32 v162, v159, v162
	v_mul_f32_e32 v163, v159, v163
	v_mul_f32_e32 v164, v159, v164
	v_mul_f32_e32 v165, v159, v165
	v_mul_f32_e32 v166, v159, v166
	v_mul_f32_e32 v167, v159, v167
	v_mul_f32_e32 v28, v28, v160
	v_mul_f32_e32 v29, v29, v161
	v_mul_f32_e32 v30, v30, v162
	v_mul_f32_e32 v31, v31, v163
	v_mul_f32_e32 v20, v20, v164
	v_mul_f32_e32 v21, v21, v165
	v_mul_f32_e32 v22, v22, v166
	v_mul_f32_e32 v23, v23, v167
	v_cvt_pk_bf16_f32 v160, v28, v29
	v_cvt_pk_bf16_f32 v161, v30, v31
	v_cvt_pk_bf16_f32 v162, v20, v21
	v_cvt_pk_bf16_f32 v163, v22, v23
	v_add_u32_e32 v144, 0xdc000, v141
	global_store_dwordx4 v144, v[160:163], s[10:11]
	s_waitcnt lgkmcnt(0)
	v_mul_f32_e32 v158, 0xbfb8aa3b, v157
	v_mul_f32_e32 v159, v157, v157
	v_mul_f32_e32 v168, v158, v12
	v_mul_f32_e32 v169, v158, v13
	v_mul_f32_e32 v170, v158, v14
	v_mul_f32_e32 v171, v158, v15
	v_mul_f32_e32 v172, v158, v4
	v_mul_f32_e32 v173, v158, v5
	v_mul_f32_e32 v174, v158, v6
	v_mul_f32_e32 v175, v158, v7
	v_exp_f32_e32 v168, v168
	v_exp_f32_e32 v169, v169
	v_exp_f32_e32 v170, v170
	v_exp_f32_e32 v171, v171
	v_exp_f32_e32 v172, v172
	v_exp_f32_e32 v173, v173
	v_exp_f32_e32 v174, v174
	v_exp_f32_e32 v175, v175
	v_add_f32_e32 v168, 1.0, v168
	v_add_f32_e32 v169, 1.0, v169
	v_add_f32_e32 v170, 1.0, v170
	v_add_f32_e32 v171, 1.0, v171
	v_add_f32_e32 v172, 1.0, v172
	v_add_f32_e32 v173, 1.0, v173
	v_add_f32_e32 v174, 1.0, v174
	v_add_f32_e32 v175, 1.0, v175
	v_rcp_f32_e32 v168, v168
	v_rcp_f32_e32 v169, v169
	v_rcp_f32_e32 v170, v170
	v_rcp_f32_e32 v171, v171
	v_rcp_f32_e32 v172, v172
	v_rcp_f32_e32 v173, v173
	v_rcp_f32_e32 v174, v174
	v_rcp_f32_e32 v175, v175
	v_mul_f32_e32 v12, v12, v8
	v_mul_f32_e32 v13, v13, v9
	v_mul_f32_e32 v14, v14, v10
	v_mul_f32_e32 v15, v15, v11
	v_mul_f32_e32 v4, v4, v0
	v_mul_f32_e32 v5, v5, v1
	v_mul_f32_e32 v6, v6, v2
	v_mul_f32_e32 v7, v7, v3
	v_mul_f32_e32 v168, v159, v168
	v_mul_f32_e32 v169, v159, v169
	v_mul_f32_e32 v170, v159, v170
	v_mul_f32_e32 v171, v159, v171
	v_mul_f32_e32 v172, v159, v172
	v_mul_f32_e32 v173, v159, v173
	v_mul_f32_e32 v174, v159, v174
	v_mul_f32_e32 v175, v159, v175
	v_mul_f32_e32 v12, v12, v168
	v_mul_f32_e32 v13, v13, v169
	v_mul_f32_e32 v14, v14, v170
	v_mul_f32_e32 v15, v15, v171
	v_mul_f32_e32 v4, v4, v172
	v_mul_f32_e32 v5, v5, v173
	v_mul_f32_e32 v6, v6, v174
	v_mul_f32_e32 v7, v7, v175
	v_cvt_pk_bf16_f32 v168, v12, v13
	v_cvt_pk_bf16_f32 v169, v14, v15
	v_cvt_pk_bf16_f32 v170, v4, v5
	v_cvt_pk_bf16_f32 v171, v6, v7
	v_add_u32_e32 v143, 0xf2000, v141
	global_store_dwordx4 v143, v[168:171], s[10:11]
	s_andn2_b64 vcc, exec, s[2:3]
	s_mov_b64 s[4:5], -1
	s_cbranch_vccnz .LBB0_1948
	s_branch .Lswi_tail

.Lswi_tail:
	s_andn2_b64 vcc, exec, s[8:9]
	s_cbranch_vccnz .LBB0_1947
	s_barrier
	s_branch .LBB0_1947
